# in-proj epilogue rewritten by hand: rope cos/sin table loads hoisted into one batch (one wait instead of 16 serial load+wait), dwordx4 stores via permlane16_swap
# speedup vs baseline: 1.0128x; 1.0128x over previous
; __device__ __forceinline__ int lane_fresh() { unsigned m = ~0u; asm volatile("" : "+s"(m)); return (int)__builtin_amdgcn_mbcnt_hi(m, __builtin_amdgcn_mbcnt_lo(m, 0u)); }
; template <class Epi>
; __device__ __forceinline__ void gemm_phase(LAS unsigned char* lds, const Gemm g, const StaticOrder& S, const Epi& E, int wv) {
;     ...
;     for (;;) {
;         const bool has_next = S.next(ui + 1, nxt);
;         const char* nA = has_next ? (const char*)g.A + (size_t)nxt.pm * tstepA : cA; const char* nB = has_next ? (const char*)g.Bt + (size_t)nxt.pn * tstepB : cB;
;     ...
;         { const int ln2 = lane_fresh();
;           E(acc, cur, wr, wc, ln2 & 15, ln2 >> 4); }
;         if (!has_next) break;
; #pragma unroll
;         for (int a = 0; a < 2; ++a)
; #pragma unroll
;             for (int b = 0; b < 2; ++b)
; #pragma unroll
;                 for (int m = 0; m < 4; ++m)
; #pragma unroll
;                     for (int n = 0; n < 2; ++n) acc[a][b][m][n] = (f32x4){0.f, 0.f, 0.f, 0.f};
;         cur = nxt; cA = nA; cB = nB; ++ui;
.LBB0_207:
	s_and_b64 vcc, exec, s[4:5]
	s_mov_b32 s8, s30
	s_mov_b32 s6, s34
	s_mov_b64 s[42:43], s[38:39]
	s_mov_b64 s[40:41], s[36:37]
	s_cbranch_vccnz .LBB0_248

; #define PG8_STAGE(bufoff, gbase, voff) do { _Pragma("unroll") for (int _i = 0; _i < 2; ++_i) \
;         __builtin_amdgcn_global_load_lds((const unsigned*)((const char*)(gbase) + (voff)[_i]), (LAS unsigned*)(lds + (bufoff) + ldsw + _i * 8192), 16, 0, 0); } while (0)
; #define PG8_LDA(dst, b, h) do { _Pragma("unroll") for (int m = 0; m < 4; ++m) _Pragma("unroll") for (int k = 0; k < 2; ++k) dst[m][k] = *(const LAS bf16x8*)(lds + PG8_SA(b, h) + aoff + m * 2048 + k * 1024); } while (0)
; #define PG8_LDB(dst, b, h) do { _Pragma("unroll") for (int n = 0; n < 2; ++n) _Pragma("unroll") for (int k = 0; k < 2; ++k) dst[n][k] = *(const LAS bf16x8*)(lds + PG8_SB(b, h) + boff + n * 2048 + k * 1024); } while (0)
; #define PG8_MMA(ai, bj, At, Bt) do { __builtin_amdgcn_s_setprio(1); _Pragma("unroll") for (int m = 0; m < 4; ++m) _Pragma("unroll") for (int n = 0; n < 2; ++n) _Pragma("unroll") for (int k = 0; k < 2; ++k) \
;         acc[ai][bj][m][n] = __builtin_amdgcn_mfma_f32_16x16x32_bf16(Bt[n][k], At[m][k], acc[ai][bj][m][n], 0, 0, 0); __builtin_amdgcn_s_setprio(0); } while (0)
; #define PG8_WAIT_V(n) asm volatile("s_waitcnt vmcnt(" #n ")" ::: "memory")
; #define PG8_WAIT_L(n) asm volatile("s_waitcnt lgkmcnt(" #n ")" ::: "memory")
; template <class Epi>
; __device__ __forceinline__ void gemm_phase(LAS unsigned char* lds, const Gemm g, const StaticOrder& S, const Epi& E, int wv) {
;     ...
;         for (int t = 0; t < nt; t += 2) {
;             const bool last = (t == nt - 2);
;             const char* a1 = cA + (size_t)(t + 1) * kstep;
;             const char* a2 = last ? nA : cA + (size_t)(t + 2) * kstep; const char* b2 = last ? nB : cB + (size_t)(t + 2) * kstep;
;             const char* a3 = a2 + kstep; const char* b3 = b2 + kstep;
;             PG8_LDB(B0, 0, 0); PG8_SCHED; PG8_LDA(At, 0, 0); PG8_STAGE(PG8_SA(1, 1), a1 + hstep, voffA);
;             PG8_WAIT_L(8); PG8_BAR; PG8_WAIT_L(0); PG8_MMA(0, 0, At, B0); PG8_BAR; PG8_SCHED;
;             PG8_LDB(B1, 0, 1); PG8_STAGE(PG8_SB(0, 0), b2, voffB);
;             PG8_BAR; PG8_WAIT_L(0); PG8_MMA(0, 1, At, B1); PG8_BAR;
;             PG8_LDA(At, 0, 1); PG8_STAGE(PG8_SA(0, 0), a2, voffA);
;             PG8_BAR; PG8_WAIT_L(0); PG8_MMA(1, 0, At, B0); PG8_BAR; PG8_SCHED;
;             PG8_STAGE(PG8_SB(0, 1), b2 + hstep, voffB);
;             PG8_WAIT_V(6); PG8_BAR; PG8_MMA(1, 1, At, B1); PG8_BAR;
.LBB0_215:
	ds_read_b128 v[146:149], v153
	ds_read_b128 v[156:159], v153 offset:1024
	ds_read_b128 v[160:163], v153 offset:2048
	ds_read_b128 v[164:167], v153 offset:3072
	s_add_u32 s42, s40, 0x100
	s_addc_u32 s43, s41, 0
	s_cmp_eq_u32 s70, 12
	s_cselect_b32 s47, s7, s43
	s_cselect_b32 s46, s9, s42
	s_cselect_b32 s45, s31, s69
	s_cselect_b32 s44, s35, s68
	v_lshl_add_u64 v[150:151], s[40:41], 0, v[138:139]
	s_add_i32 m0, s50, 0xc000
	ds_read_b128 v[168:171], v154
	ds_read_b128 v[172:175], v154 offset:1024
	ds_read_b128 v[176:179], v154 offset:2048
	ds_read_b128 v[180:183], v154 offset:3072
	ds_read_b128 v[184:187], v154 offset:4096
	ds_read_b128 v[188:191], v154 offset:5120
	ds_read_b128 v[192:195], v154 offset:6144
	ds_read_b128 v[196:199], v154 offset:7168
	global_load_lds_dwordx4 v[150:151], off
	v_lshl_add_u64 v[150:151], s[40:41], 0, v[140:141]
	s_add_i32 m0, s50, 0xe000
	s_nop 0
	global_load_lds_dwordx4 v[150:151], off
	s_waitcnt lgkmcnt(8)
	s_barrier
	s_waitcnt lgkmcnt(0)
	s_setprio 1
	s_waitcnt lgkmcnt(0)
	v_mfma_f32_16x16x32_bf16 v[124:127], v[146:149], v[168:171], v[124:127]
	v_mfma_f32_16x16x32_bf16 v[120:123], v[160:163], v[168:171], v[120:123]
	v_mfma_f32_16x16x32_bf16 v[108:111], v[146:149], v[176:179], v[108:111]
	v_mfma_f32_16x16x32_bf16 v[104:107], v[160:163], v[176:179], v[104:107]
	v_mfma_f32_16x16x32_bf16 v[92:95], v[146:149], v[184:187], v[92:95]
	v_mfma_f32_16x16x32_bf16 v[88:91], v[160:163], v[184:187], v[88:91]
	v_mfma_f32_16x16x32_bf16 v[76:79], v[146:149], v[192:195], v[76:79]
	v_mfma_f32_16x16x32_bf16 v[72:75], v[160:163], v[192:195], v[72:75]
	v_mfma_f32_16x16x32_bf16 v[124:127], v[156:159], v[172:175], v[124:127]
	v_mfma_f32_16x16x32_bf16 v[120:123], v[164:167], v[172:175], v[120:123]
	v_mfma_f32_16x16x32_bf16 v[108:111], v[156:159], v[180:183], v[108:111]
	v_mfma_f32_16x16x32_bf16 v[104:107], v[164:167], v[180:183], v[104:107]
	v_mfma_f32_16x16x32_bf16 v[92:95], v[156:159], v[188:191], v[92:95]
	v_mfma_f32_16x16x32_bf16 v[88:91], v[164:167], v[188:191], v[88:91]
	v_mfma_f32_16x16x32_bf16 v[76:79], v[156:159], v[196:199], v[76:79]
	v_mfma_f32_16x16x32_bf16 v[72:75], v[164:167], v[196:199], v[72:75]
	s_setprio 0
	s_barrier
	s_add_i32 s40, s65, s49
	v_lshl_add_u64 v[150:151], s[44:45], 0, v[130:131]
	s_mov_b32 m0, s40
	ds_read_b128 v[200:203], v155
	ds_read_b128 v[204:207], v155 offset:1024
	ds_read_b128 v[208:211], v155 offset:2048
	ds_read_b128 v[212:215], v155 offset:3072
	global_load_lds_dwordx4 v[150:151], off
	v_lshl_add_u64 v[216:217], s[44:45], 0, v[134:135]
	s_add_i32 m0, s40, 0x2000
	s_nop 0
	global_load_lds_dwordx4 v[216:217], off
	s_barrier
	s_waitcnt lgkmcnt(0)
	s_setprio 1
	s_waitcnt lgkmcnt(0)
	v_mfma_f32_16x16x32_bf16 v[116:119], v[200:203], v[168:171], v[116:119]
	v_mfma_f32_16x16x32_bf16 v[112:115], v[208:211], v[168:171], v[112:115]
	v_mfma_f32_16x16x32_bf16 v[100:103], v[200:203], v[176:179], v[100:103]
	v_mfma_f32_16x16x32_bf16 v[96:99], v[208:211], v[176:179], v[96:99]
	v_mfma_f32_16x16x32_bf16 v[84:87], v[200:203], v[184:187], v[84:87]
	v_mfma_f32_16x16x32_bf16 v[80:83], v[208:211], v[184:187], v[80:83]
	v_mfma_f32_16x16x32_bf16 v[68:71], v[200:203], v[192:195], v[68:71]
	v_mfma_f32_16x16x32_bf16 v[64:67], v[208:211], v[192:195], v[64:67]
	v_mfma_f32_16x16x32_bf16 v[116:119], v[204:207], v[172:175], v[116:119]
	v_mfma_f32_16x16x32_bf16 v[112:115], v[212:215], v[172:175], v[112:115]
	v_mfma_f32_16x16x32_bf16 v[100:103], v[204:207], v[180:183], v[100:103]
	v_mfma_f32_16x16x32_bf16 v[96:99], v[212:215], v[180:183], v[96:99]
	v_mfma_f32_16x16x32_bf16 v[84:87], v[204:207], v[188:191], v[84:87]
	v_mfma_f32_16x16x32_bf16 v[80:83], v[212:215], v[188:191], v[80:83]
	v_mfma_f32_16x16x32_bf16 v[68:71], v[204:207], v[196:199], v[68:71]
	v_mfma_f32_16x16x32_bf16 v[64:67], v[212:215], v[196:199], v[64:67]
	s_setprio 0
	s_mov_b32 m0, s50
	v_lshl_add_u64 v[218:219], s[46:47], 0, v[128:129]
	s_barrier
	ds_read_b128 v[168:171], v154 offset:16384
	ds_read_b128 v[172:175], v154 offset:17408
	ds_read_b128 v[176:179], v154 offset:18432
	ds_read_b128 v[180:183], v154 offset:19456
	ds_read_b128 v[184:187], v154 offset:20480
	ds_read_b128 v[188:191], v154 offset:21504
	ds_read_b128 v[192:195], v154 offset:22528
	ds_read_b128 v[196:199], v154 offset:23552
	global_load_lds_dwordx4 v[218:219], off
	v_lshl_add_u64 v[220:221], s[46:47], 0, v[132:133]
	s_mov_b32 m0, s51
	s_nop 0
	global_load_lds_dwordx4 v[220:221], off
	s_barrier
	s_waitcnt lgkmcnt(0)
	s_setprio 1
	s_waitcnt lgkmcnt(0)
	v_mfma_f32_16x16x32_bf16 v[60:63], v[146:149], v[168:171], v[60:63]
	v_mfma_f32_16x16x32_bf16 v[56:59], v[160:163], v[168:171], v[56:59]
	v_mfma_f32_16x16x32_bf16 v[44:47], v[146:149], v[176:179], v[44:47]
	v_mfma_f32_16x16x32_bf16 v[40:43], v[160:163], v[176:179], v[40:43]
	v_mfma_f32_16x16x32_bf16 v[28:31], v[146:149], v[184:187], v[28:31]
	v_mfma_f32_16x16x32_bf16 v[24:27], v[160:163], v[184:187], v[24:27]
	v_mfma_f32_16x16x32_bf16 v[12:15], v[146:149], v[192:195], v[12:15]
	v_mfma_f32_16x16x32_bf16 v[8:11], v[160:163], v[192:195], v[8:11]
	v_mfma_f32_16x16x32_bf16 v[60:63], v[156:159], v[172:175], v[60:63]
	v_mfma_f32_16x16x32_bf16 v[56:59], v[164:167], v[172:175], v[56:59]
	v_mfma_f32_16x16x32_bf16 v[44:47], v[156:159], v[180:183], v[44:47]
	v_mfma_f32_16x16x32_bf16 v[40:43], v[164:167], v[180:183], v[40:43]
	v_mfma_f32_16x16x32_bf16 v[28:31], v[156:159], v[188:191], v[28:31]
	v_mfma_f32_16x16x32_bf16 v[24:27], v[164:167], v[188:191], v[24:27]
	v_mfma_f32_16x16x32_bf16 v[12:15], v[156:159], v[196:199], v[12:15]
	v_mfma_f32_16x16x32_bf16 v[8:11], v[164:167], v[196:199], v[8:11]
	s_setprio 0
	s_barrier
; #define PG8_STAGE(bufoff, gbase, voff) do { _Pragma("unroll") for (int _i = 0; _i < 2; ++_i) \
;         __builtin_amdgcn_global_load_lds((const unsigned*)((const char*)(gbase) + (voff)[_i]), (LAS unsigned*)(lds + (bufoff) + ldsw + _i * 8192), 16, 0, 0); } while (0)
; #define PG8_LDA(dst, b, h) do { _Pragma("unroll") for (int m = 0; m < 4; ++m) _Pragma("unroll") for (int k = 0; k < 2; ++k) dst[m][k] = *(const LAS bf16x8*)(lds + PG8_SA(b, h) + aoff + m * 2048 + k * 1024); } while (0)
; #define PG8_LDB(dst, b, h) do { _Pragma("unroll") for (int n = 0; n < 2; ++n) _Pragma("unroll") for (int k = 0; k < 2; ++k) dst[n][k] = *(const LAS bf16x8*)(lds + PG8_SB(b, h) + boff + n * 2048 + k * 1024); } while (0)
; #define PG8_MMA(ai, bj, At, Bt) do { __builtin_amdgcn_s_setprio(1); _Pragma("unroll") for (int m = 0; m < 4; ++m) _Pragma("unroll") for (int n = 0; n < 2; ++n) _Pragma("unroll") for (int k = 0; k < 2; ++k) \
;         acc[ai][bj][m][n] = __builtin_amdgcn_mfma_f32_16x16x32_bf16(Bt[n][k], At[m][k], acc[ai][bj][m][n], 0, 0, 0); __builtin_amdgcn_s_setprio(0); } while (0)
; #define PG8_WAIT_V(n) asm volatile("s_waitcnt vmcnt(" #n ")" ::: "memory")
; #define PG8_WAIT_L(n) asm volatile("s_waitcnt lgkmcnt(" #n ")" ::: "memory")
; #define PG8_BAR __builtin_amdgcn_s_barrier()
; #define PG8_SCHED __builtin_amdgcn_sched_barrier(0)
; template <class Epi>
; __device__ __forceinline__ void gemm_phase(LAS unsigned char* lds, const Gemm g, const StaticOrder& S, const Epi& E, int wv) {
;     ...
;             PG8_LDA(At, 0, 1); PG8_STAGE(PG8_SA(0, 0), a2, voffA);
;             PG8_BAR; PG8_WAIT_L(0); PG8_MMA(1, 0, At, B0); PG8_BAR; PG8_SCHED;
;             PG8_STAGE(PG8_SB(0, 1), b2 + hstep, voffB);
;             PG8_WAIT_V(6); PG8_BAR; PG8_MMA(1, 1, At, B1); PG8_BAR;
;             PG8_LDB(B0, 1, 0); PG8_SCHED; PG8_LDA(At, 1, 0); PG8_STAGE(PG8_SA(0, 1), a2 + hstep, voffA);
;             PG8_WAIT_L(8); PG8_BAR; PG8_WAIT_L(0); PG8_MMA(0, 0, At, B0); PG8_BAR; PG8_SCHED;
;             PG8_LDB(B1, 1, 1); PG8_STAGE(PG8_SB(1, 0), b3, voffB);
;             PG8_BAR; PG8_WAIT_L(0); PG8_MMA(0, 1, At, B1); PG8_BAR;
;             PG8_LDA(At, 1, 1); PG8_STAGE(PG8_SA(1, 0), a3, voffA);
;             PG8_BAR; PG8_WAIT_L(0); PG8_MMA(1, 0, At, B0); PG8_BAR; PG8_SCHED;
	s_add_u32 s40, s44, 0x40000
	s_addc_u32 s41, s45, 0
	s_add_i32 s71, s66, s49
	v_lshl_add_u64 v[146:147], s[40:41], 0, v[130:131]
	s_mov_b32 m0, s71
	s_nop 0
	global_load_lds_dwordx4 v[146:147], off
	v_lshl_add_u64 v[146:147], s[40:41], 0, v[134:135]
	s_add_i32 m0, s71, 0x2000
	s_nop 0
	global_load_lds_dwordx4 v[146:147], off
	s_waitcnt vmcnt(6)
	s_barrier
	s_setprio 1
	v_mfma_f32_16x16x32_bf16 v[52:55], v[200:203], v[168:171], v[52:55]
	v_mfma_f32_16x16x32_bf16 v[48:51], v[208:211], v[168:171], v[48:51]
	v_mfma_f32_16x16x32_bf16 v[36:39], v[200:203], v[176:179], v[36:39]
	v_mfma_f32_16x16x32_bf16 v[32:35], v[208:211], v[176:179], v[32:35]
	v_mfma_f32_16x16x32_bf16 v[20:23], v[200:203], v[184:187], v[20:23]
	v_mfma_f32_16x16x32_bf16 v[16:19], v[208:211], v[184:187], v[16:19]
	v_mfma_f32_16x16x32_bf16 v[4:7], v[200:203], v[192:195], v[4:7]
	v_mfma_f32_16x16x32_bf16 v[0:3], v[208:211], v[192:195], v[0:3]
	v_mfma_f32_16x16x32_bf16 v[52:55], v[204:207], v[172:175], v[52:55]
	v_mfma_f32_16x16x32_bf16 v[48:51], v[212:215], v[172:175], v[48:51]
	v_mfma_f32_16x16x32_bf16 v[36:39], v[204:207], v[180:183], v[36:39]
	v_mfma_f32_16x16x32_bf16 v[32:35], v[212:215], v[180:183], v[32:35]
	v_mfma_f32_16x16x32_bf16 v[20:23], v[204:207], v[188:191], v[20:23]
	v_mfma_f32_16x16x32_bf16 v[16:19], v[212:215], v[188:191], v[16:19]
	v_mfma_f32_16x16x32_bf16 v[4:7], v[204:207], v[196:199], v[4:7]
	v_mfma_f32_16x16x32_bf16 v[0:3], v[212:215], v[196:199], v[0:3]
	s_setprio 0
	s_add_i32 s71, 0, 0x18000
	v_add_u32_e32 v136, s71, v152
	s_barrier
	ds_read_b128 v[146:149], v136
	ds_read_b128 v[156:159], v136 offset:1024
	ds_read_b128 v[160:163], v136 offset:2048
	ds_read_b128 v[164:167], v136 offset:3072
	s_add_u32 s40, s46, 0x40000
	s_addc_u32 s41, s47, 0
	s_mov_b32 m0, s52
	v_lshl_add_u64 v[200:201], s[40:41], 0, v[128:129]
	ds_read_b128 v[168:171], v154 offset:32768
	ds_read_b128 v[172:175], v154 offset:33792
	ds_read_b128 v[176:179], v154 offset:34816
	ds_read_b128 v[180:183], v154 offset:35840
	ds_read_b128 v[184:187], v154 offset:36864
	ds_read_b128 v[188:191], v154 offset:37888
	ds_read_b128 v[192:195], v154 offset:38912
	ds_read_b128 v[196:199], v154 offset:39936
	global_load_lds_dwordx4 v[200:201], off
	v_lshl_add_u64 v[200:201], s[40:41], 0, v[132:133]
	s_mov_b32 m0, s53
	s_nop 0
	global_load_lds_dwordx4 v[200:201], off
	s_waitcnt lgkmcnt(8)
	s_barrier
	s_waitcnt lgkmcnt(0)
	s_setprio 1
	s_waitcnt lgkmcnt(0)
	v_mfma_f32_16x16x32_bf16 v[124:127], v[146:149], v[168:171], v[124:127]
	v_mfma_f32_16x16x32_bf16 v[120:123], v[160:163], v[168:171], v[120:123]
	v_mfma_f32_16x16x32_bf16 v[108:111], v[146:149], v[176:179], v[108:111]
	v_mfma_f32_16x16x32_bf16 v[104:107], v[160:163], v[176:179], v[104:107]
	v_mfma_f32_16x16x32_bf16 v[92:95], v[146:149], v[184:187], v[92:95]
	v_mfma_f32_16x16x32_bf16 v[88:91], v[160:163], v[184:187], v[88:91]
	v_mfma_f32_16x16x32_bf16 v[76:79], v[146:149], v[192:195], v[76:79]
	v_mfma_f32_16x16x32_bf16 v[72:75], v[160:163], v[192:195], v[72:75]
	v_mfma_f32_16x16x32_bf16 v[124:127], v[156:159], v[172:175], v[124:127]
	v_mfma_f32_16x16x32_bf16 v[120:123], v[164:167], v[172:175], v[120:123]
	v_mfma_f32_16x16x32_bf16 v[108:111], v[156:159], v[180:183], v[108:111]
	v_mfma_f32_16x16x32_bf16 v[104:107], v[164:167], v[180:183], v[104:107]
	v_mfma_f32_16x16x32_bf16 v[92:95], v[156:159], v[188:191], v[92:95]
	v_mfma_f32_16x16x32_bf16 v[88:91], v[164:167], v[188:191], v[88:91]
	v_mfma_f32_16x16x32_bf16 v[76:79], v[156:159], v[196:199], v[76:79]
	v_mfma_f32_16x16x32_bf16 v[72:75], v[164:167], v[196:199], v[72:75]
	s_setprio 0
	s_barrier
	s_add_i32 s46, 0, 0x1c000
	s_add_i32 s40, s71, s49
	v_add_u32_e32 v136, s46, v152
	v_lshl_add_u64 v[150:151], v[150:151], 0, s[28:29]
	s_mov_b32 m0, s40
	ds_read_b128 v[200:203], v136
	ds_read_b128 v[204:207], v136 offset:1024
	ds_read_b128 v[208:211], v136 offset:2048
	ds_read_b128 v[212:215], v136 offset:3072
	global_load_lds_dwordx4 v[150:151], off
	v_lshl_add_u64 v[150:151], v[216:217], 0, s[28:29]
	s_add_i32 m0, s40, 0x2000
	s_nop 0
	global_load_lds_dwordx4 v[150:151], off
	s_barrier
	s_waitcnt lgkmcnt(0)
	s_setprio 1
	s_waitcnt lgkmcnt(0)
	v_mfma_f32_16x16x32_bf16 v[116:119], v[200:203], v[168:171], v[116:119]
	v_mfma_f32_16x16x32_bf16 v[112:115], v[208:211], v[168:171], v[112:115]
	v_mfma_f32_16x16x32_bf16 v[100:103], v[200:203], v[176:179], v[100:103]
	v_mfma_f32_16x16x32_bf16 v[96:99], v[208:211], v[176:179], v[96:99]
	v_mfma_f32_16x16x32_bf16 v[84:87], v[200:203], v[184:187], v[84:87]
	v_mfma_f32_16x16x32_bf16 v[80:83], v[208:211], v[184:187], v[80:83]
	v_mfma_f32_16x16x32_bf16 v[68:71], v[200:203], v[192:195], v[68:71]
	v_mfma_f32_16x16x32_bf16 v[64:67], v[208:211], v[192:195], v[64:67]
	v_mfma_f32_16x16x32_bf16 v[116:119], v[204:207], v[172:175], v[116:119]
	v_mfma_f32_16x16x32_bf16 v[112:115], v[212:215], v[172:175], v[112:115]
	v_mfma_f32_16x16x32_bf16 v[100:103], v[204:207], v[180:183], v[100:103]
	v_mfma_f32_16x16x32_bf16 v[96:99], v[212:215], v[180:183], v[96:99]
	v_mfma_f32_16x16x32_bf16 v[84:87], v[204:207], v[188:191], v[84:87]
	v_mfma_f32_16x16x32_bf16 v[80:83], v[212:215], v[188:191], v[80:83]
	v_mfma_f32_16x16x32_bf16 v[68:71], v[204:207], v[196:199], v[68:71]
	v_mfma_f32_16x16x32_bf16 v[64:67], v[212:215], v[196:199], v[64:67]
	s_setprio 0
	s_mov_b32 m0, s58
	v_lshl_add_u64 v[150:151], v[218:219], 0, s[28:29]
	s_barrier
	ds_read_b128 v[168:171], v154 offset:49152
	ds_read_b128 v[172:175], v154 offset:50176
	ds_read_b128 v[176:179], v154 offset:51200
	ds_read_b128 v[180:183], v154 offset:52224
	ds_read_b128 v[184:187], v154 offset:53248
	ds_read_b128 v[188:191], v154 offset:54272
	ds_read_b128 v[192:195], v154 offset:55296
	ds_read_b128 v[196:199], v154 offset:56320
	global_load_lds_dwordx4 v[150:151], off
	v_lshl_add_u64 v[150:151], v[220:221], 0, s[28:29]
	s_mov_b32 m0, s59
	s_nop 0
	global_load_lds_dwordx4 v[150:151], off
	s_barrier
; #define PG8_STAGE(bufoff, gbase, voff) do { _Pragma("unroll") for (int _i = 0; _i < 2; ++_i) \
;         __builtin_amdgcn_global_load_lds((const unsigned*)((const char*)(gbase) + (voff)[_i]), (LAS unsigned*)(lds + (bufoff) + ldsw + _i * 8192), 16, 0, 0); } while (0)
; #define PG8_MMA(ai, bj, At, Bt) do { __builtin_amdgcn_s_setprio(1); _Pragma("unroll") for (int m = 0; m < 4; ++m) _Pragma("unroll") for (int n = 0; n < 2; ++n) _Pragma("unroll") for (int k = 0; k < 2; ++k) \
;         acc[ai][bj][m][n] = __builtin_amdgcn_mfma_f32_16x16x32_bf16(Bt[n][k], At[m][k], acc[ai][bj][m][n], 0, 0, 0); __builtin_amdgcn_s_setprio(0); } while (0)
; #define PG8_WAIT_V(n) asm volatile("s_waitcnt vmcnt(" #n ")" ::: "memory")
; #define PG8_WAIT_L(n) asm volatile("s_waitcnt lgkmcnt(" #n ")" ::: "memory")
; #define PG8_BAR __builtin_amdgcn_s_barrier()
; #define PG8_SCHED __builtin_amdgcn_sched_barrier(0)
; template <class Epi>
; __device__ __forceinline__ void gemm_phase(LAS unsigned char* lds, const Gemm g, const StaticOrder& S, const Epi& E, int wv) {
;     ...
;             PG8_BAR; PG8_WAIT_L(0); PG8_MMA(1, 0, At, B0); PG8_BAR; PG8_SCHED;
;             PG8_STAGE(PG8_SB(1, 1), b3 + hstep, voffB);
;             PG8_WAIT_V(6); PG8_BAR; PG8_MMA(1, 1, At, B1); PG8_BAR;
;         }
;     __device__ __forceinline__ void operator()(const f32x4 (&acc)[2][2][4][2], const Unit& u, int wr, int wc, int fr, int fq) const {
;         const bool latent = u.pm < 128;
; #pragma unroll
;         for (int ai = 0; ai < 2; ++ai)
; #pragma unroll
;             for (int m = 0; m < 4; ++m) {
;                 const int row = u.pm * 256 + ai * 128 + wr * 64 + 4 * fr + m;
;                 const int t = row & (S - 1);
;                 const int pos = (wc & 1) ? (t & 63) : (t >> 6);
; #pragma unroll
;                 for (int bj = 0; bj < 2; ++bj) {
;                     const int col = u.pn * 256 + bj * 128 + wc * 32 + 4 * fq;
;                     f32x4 v0 = acc[ai][bj][m][0], v1 = acc[ai][bj][m][1];
;                     const bool rope = latent && (u.pn == 4 || u.pn == 5 || (u.pn == 6 && bj == 0));
;                     if (rope) {
;                         const f32x4 cs = *(const f32x4*)(cosT + pos * 16 + 4 * fq), sn = *(const f32x4*)(sinT + pos * 16 + 4 * fq);
	s_waitcnt lgkmcnt(0)
	s_setprio 1
	s_waitcnt lgkmcnt(0)
	v_mfma_f32_16x16x32_bf16 v[60:63], v[146:149], v[168:171], v[60:63]
	v_mfma_f32_16x16x32_bf16 v[56:59], v[160:163], v[168:171], v[56:59]
	v_mfma_f32_16x16x32_bf16 v[44:47], v[146:149], v[176:179], v[44:47]
	v_mfma_f32_16x16x32_bf16 v[40:43], v[160:163], v[176:179], v[40:43]
	v_mfma_f32_16x16x32_bf16 v[28:31], v[146:149], v[184:187], v[28:31]
	v_mfma_f32_16x16x32_bf16 v[24:27], v[160:163], v[184:187], v[24:27]
	v_mfma_f32_16x16x32_bf16 v[12:15], v[146:149], v[192:195], v[12:15]
	v_mfma_f32_16x16x32_bf16 v[8:11], v[160:163], v[192:195], v[8:11]
	v_mfma_f32_16x16x32_bf16 v[60:63], v[156:159], v[172:175], v[60:63]
	v_mfma_f32_16x16x32_bf16 v[56:59], v[164:167], v[172:175], v[56:59]
	v_mfma_f32_16x16x32_bf16 v[44:47], v[156:159], v[180:183], v[44:47]
	v_mfma_f32_16x16x32_bf16 v[40:43], v[164:167], v[180:183], v[40:43]
	v_mfma_f32_16x16x32_bf16 v[28:31], v[156:159], v[188:191], v[28:31]
	v_mfma_f32_16x16x32_bf16 v[24:27], v[164:167], v[188:191], v[24:27]
	v_mfma_f32_16x16x32_bf16 v[12:15], v[156:159], v[196:199], v[12:15]
	v_mfma_f32_16x16x32_bf16 v[8:11], v[164:167], v[196:199], v[8:11]
	s_setprio 0
	s_barrier
	s_add_u32 s40, s44, 0x40080
	s_addc_u32 s41, s45, 0
	s_add_i32 s44, s46, s49
	v_lshl_add_u64 v[146:147], s[40:41], 0, v[130:131]
	s_mov_b32 m0, s44
	s_nop 0
	global_load_lds_dwordx4 v[146:147], off
	v_lshl_add_u64 v[146:147], s[40:41], 0, v[134:135]
	s_add_i32 m0, s44, 0x2000
	s_nop 0
	global_load_lds_dwordx4 v[146:147], off
	s_waitcnt vmcnt(6)
	s_barrier
	s_setprio 1
	v_mfma_f32_16x16x32_bf16 v[52:55], v[200:203], v[168:171], v[52:55]
	v_mfma_f32_16x16x32_bf16 v[48:51], v[208:211], v[168:171], v[48:51]
	v_mfma_f32_16x16x32_bf16 v[36:39], v[200:203], v[176:179], v[36:39]
	v_mfma_f32_16x16x32_bf16 v[32:35], v[208:211], v[176:179], v[32:35]
	v_mfma_f32_16x16x32_bf16 v[20:23], v[200:203], v[184:187], v[20:23]
	v_mfma_f32_16x16x32_bf16 v[16:19], v[208:211], v[184:187], v[16:19]
	v_mfma_f32_16x16x32_bf16 v[4:7], v[200:203], v[192:195], v[4:7]
	v_mfma_f32_16x16x32_bf16 v[0:3], v[208:211], v[192:195], v[0:3]
	v_mfma_f32_16x16x32_bf16 v[52:55], v[204:207], v[172:175], v[52:55]
	v_mfma_f32_16x16x32_bf16 v[48:51], v[212:215], v[172:175], v[48:51]
	v_mfma_f32_16x16x32_bf16 v[36:39], v[204:207], v[180:183], v[36:39]
	v_mfma_f32_16x16x32_bf16 v[32:35], v[212:215], v[180:183], v[32:35]
	v_mfma_f32_16x16x32_bf16 v[20:23], v[204:207], v[188:191], v[20:23]
	v_mfma_f32_16x16x32_bf16 v[16:19], v[212:215], v[188:191], v[16:19]
	v_mfma_f32_16x16x32_bf16 v[4:7], v[204:207], v[196:199], v[4:7]
	v_mfma_f32_16x16x32_bf16 v[0:3], v[212:215], v[196:199], v[0:3]
	s_setprio 0
	s_add_i32 s70, s70, 2
	s_add_u32 s68, s68, 0x100
	s_addc_u32 s69, s69, 0
	s_cmp_gt_u32 s70, 13
	s_mov_b64 s[40:41], s[42:43]
	s_barrier
	s_cbranch_scc0 .LBB0_215
	s_cmpk_lt_i32 s6, 0x80
	s_cselect_b64 s[40:41], -1, 0
	s_lshl_b32 s31, s6, 8
	s_add_i32 s31, s31, s55
	s_mov_b32 s7, -1
	v_mbcnt_lo_u32_b32 v136, s7, 0
	v_mbcnt_hi_u32_b32 v136, s7, v136
	s_add_i32 s6, s8, -4
	s_cmp_lt_u32 s6, 3
	s_cselect_b64 s[6:7], -1, 0
	s_and_b64 s[42:43], s[40:41], s[6:7]
	s_and_b32 s9, s8, -2
	s_cmp_eq_u32 s9, 4
	s_cselect_b64 s[6:7], -1, 0
	s_and_b64 s[40:41], s[40:41], s[6:7]
	v_lshlrev_b32_e32 v146, 2, v136
	v_and_b32_e32 v156, 60, v146
	v_lshrrev_b32_e32 v147, 2, v136
	v_and_b32_e32 v148, 28, v147
	v_bfe_u32 v222, v136, 5, 1
	v_bfe_u32 v223, v136, 4, 1
	v_lshlrev_b32_e32 v222, 4, v222
	v_lshl_or_b32 v222, v223, 5, v222
	s_lshl_b32 s9, s8, 8
	s_or_b32 s9, s9, s57
	s_lshl_b32 s9, s9, 1
	v_add_u32_e32 v222, s9, v222
	v_or_b32_e32 v157, s31, v156
	v_mul_lo_u32 v150, v157, s67
	v_add_u32_e32 v150, v150, v222
	v_mov_b32_e32 v151, 0
	v_lshl_add_u64 v[224:225], s[18:19], 0, v[150:151]
	s_mov_b64 s[6:7], 0x1c00
	v_lshl_add_u64 v[226:227], v[224:225], 0, s[6:7]
	s_mov_b64 s[6:7], 0x70000
	v_lshl_add_u64 v[228:229], v[224:225], 0, s[6:7]
	s_mov_b64 s[6:7], 0x71c00
	v_lshl_add_u64 v[230:231], v[224:225], 0, s[6:7]
	s_and_b64 vcc, exec, s[42:43]
	s_cbranch_vccz .Lproj_norope
	s_bfe_u32 s35, s31, 0x80006
	s_add_i32 s9, s31, 0x80
	s_bfe_u32 s9, s9, 0x80006
	v_lshlrev_b32_e32 v232, 2, v148
	v_mov_b32_e32 v234, s35
	v_cndmask_b32_e64 v240, v156, v234, s[10:11]
	v_lshl_add_u32 v240, v240, 6, v232
	global_load_dwordx4 v[158:161], v240, s[22:23]
	global_load_dwordx4 v[162:165], v240, s[20:21]
	v_or_b32_e32 v241, 1, v156
	v_cndmask_b32_e64 v241, v241, v234, s[10:11]
	v_lshl_add_u32 v241, v241, 6, v232
	global_load_dwordx4 v[166:169], v241, s[22:23]
	global_load_dwordx4 v[170:173], v241, s[20:21]
	v_or_b32_e32 v242, 2, v156
	v_cndmask_b32_e64 v242, v242, v234, s[10:11]
	v_lshl_add_u32 v242, v242, 6, v232
	global_load_dwordx4 v[174:177], v242, s[22:23]
	global_load_dwordx4 v[178:181], v242, s[20:21]
	v_or_b32_e32 v243, 3, v156
	v_cndmask_b32_e64 v243, v243, v234, s[10:11]
	v_lshl_add_u32 v243, v243, 6, v232
	global_load_dwordx4 v[182:185], v243, s[22:23]
	global_load_dwordx4 v[186:189], v243, s[20:21]
	v_mov_b32_e32 v234, s9
	v_cndmask_b32_e64 v244, v156, v234, s[10:11]
	v_lshl_add_u32 v244, v244, 6, v232
	global_load_dwordx4 v[190:193], v244, s[22:23]
	global_load_dwordx4 v[194:197], v244, s[20:21]
	v_or_b32_e32 v245, 1, v156
	v_cndmask_b32_e64 v245, v245, v234, s[10:11]
	v_lshl_add_u32 v245, v245, 6, v232
	global_load_dwordx4 v[198:201], v245, s[22:23]
	global_load_dwordx4 v[202:205], v245, s[20:21]
	v_or_b32_e32 v246, 2, v156
	v_cndmask_b32_e64 v246, v246, v234, s[10:11]
	v_lshl_add_u32 v246, v246, 6, v232
	global_load_dwordx4 v[206:209], v246, s[22:23]
	global_load_dwordx4 v[210:213], v246, s[20:21]
	v_or_b32_e32 v247, 3, v156
	v_cndmask_b32_e64 v247, v247, v234, s[10:11]
	v_lshl_add_u32 v247, v247, 6, v232
	global_load_dwordx4 v[214:217], v247, s[22:23]
	global_load_dwordx4 v[218:221], v247, s[20:21]
	s_waitcnt vmcnt(0)
; __device__ __forceinline__ unsigned pk2(float lo, float hi) { unsigned r; asm("v_cvt_pk_bf16_f32 %0, %1, %2" : "=v"(r) : "v"(lo), "v"(hi)); return r; }
;     __device__ __forceinline__ void operator()(const f32x4 (&acc)[2][2][4][2], const Unit& u, int wr, int wc, int fr, int fq) const {
;     ...
;                 for (int bj = 0; bj < 2; ++bj) {
;                     const int col = u.pn * 256 + bj * 128 + wc * 32 + 4 * fq;
;                     f32x4 v0 = acc[ai][bj][m][0], v1 = acc[ai][bj][m][1];
;                     const bool rope = latent && (u.pn == 4 || u.pn == 5 || (u.pn == 6 && bj == 0));
;                     if (rope) {
;                         const f32x4 cs = *(const f32x4*)(cosT + pos * 16 + 4 * fq), sn = *(const f32x4*)(sinT + pos * 16 + 4 * fq);
;                         const f32x4 n0 = v0 * cs - v1 * sn, n1 = v1 * cs + v0 * sn; v0 = n0; v1 = n1;
;                     }
;                     bf16_t* p = O + (size_t)row * DIN + col;
;                     u32x2 w0, w1; w0.x = pk2(v0[0], v0[1]); w0.y = pk2(v0[2], v0[3]); w1.x = pk2(v1[0], v1[1]); w1.y = pk2(v1[2], v1[3]);
;                     *(u32x2*)p = w0; *(u32x2*)(p + 16) = w1;
.Lproj_norope:
	s_cmp_lg_u64 s[40:41], 0
	s_cbranch_vccz .Lproj_nr_0
	v_pk_mul_f32 v[232:233], v[122:123], v[160:161]
	v_pk_mul_f32 v[234:235], v[120:121], v[158:159]
	v_pk_mul_f32 v[236:237], v[126:127], v[160:161]
	v_pk_mul_f32 v[238:239], v[124:125], v[158:159]
	v_pk_fma_f32 v[126:127], v[126:127], v[164:165], v[232:233] neg_lo:[0,0,1] neg_hi:[0,0,1]
	v_pk_fma_f32 v[124:125], v[124:125], v[162:163], v[234:235] neg_lo:[0,0,1] neg_hi:[0,0,1]
	v_pk_fma_f32 v[122:123], v[122:123], v[164:165], v[236:237]
	v_pk_fma_f32 v[120:121], v[120:121], v[162:163], v[238:239]
.Lproj_nr_0:
	v_cvt_pk_bf16_f32 v124, v124, v125
	v_cvt_pk_bf16_f32 v125, v126, v127
	v_cvt_pk_bf16_f32 v126, v120, v121
	v_cvt_pk_bf16_f32 v127, v122, v123
	s_nop 1
	v_permlane16_swap_b32_e32 v124, v126
	v_permlane16_swap_b32_e32 v125, v127
	global_store_dwordx4 v[224:225], v[124:127], off
	s_cbranch_scc0 .Lproj_nr_1
	v_pk_mul_f32 v[232:233], v[114:115], v[160:161]
	v_pk_mul_f32 v[234:235], v[112:113], v[158:159]
	v_pk_mul_f32 v[236:237], v[118:119], v[160:161]
	v_pk_mul_f32 v[238:239], v[116:117], v[158:159]
	v_pk_fma_f32 v[118:119], v[118:119], v[164:165], v[232:233] neg_lo:[0,0,1] neg_hi:[0,0,1]
	v_pk_fma_f32 v[116:117], v[116:117], v[162:163], v[234:235] neg_lo:[0,0,1] neg_hi:[0,0,1]
	v_pk_fma_f32 v[114:115], v[114:115], v[164:165], v[236:237]
	v_pk_fma_f32 v[112:113], v[112:113], v[162:163], v[238:239]
.Lproj_nr_1:
	v_cvt_pk_bf16_f32 v116, v116, v117
	v_cvt_pk_bf16_f32 v117, v118, v119
	v_cvt_pk_bf16_f32 v118, v112, v113
	v_cvt_pk_bf16_f32 v119, v114, v115
	s_nop 1
	v_permlane16_swap_b32_e32 v116, v118
	v_permlane16_swap_b32_e32 v117, v119
	global_store_dwordx4 v[224:225], v[116:119], off offset:256
	s_cbranch_vccz .Lproj_nr_2
	v_pk_mul_f32 v[232:233], v[106:107], v[168:169]
	v_pk_mul_f32 v[234:235], v[104:105], v[166:167]
	v_pk_mul_f32 v[236:237], v[110:111], v[168:169]
	v_pk_mul_f32 v[238:239], v[108:109], v[166:167]
	v_pk_fma_f32 v[110:111], v[110:111], v[172:173], v[232:233] neg_lo:[0,0,1] neg_hi:[0,0,1]
	v_pk_fma_f32 v[108:109], v[108:109], v[170:171], v[234:235] neg_lo:[0,0,1] neg_hi:[0,0,1]
	v_pk_fma_f32 v[106:107], v[106:107], v[172:173], v[236:237]
	v_pk_fma_f32 v[104:105], v[104:105], v[170:171], v[238:239]
.Lproj_nr_2:
	v_cvt_pk_bf16_f32 v108, v108, v109
	v_cvt_pk_bf16_f32 v109, v110, v111
	v_cvt_pk_bf16_f32 v110, v104, v105
	v_cvt_pk_bf16_f32 v111, v106, v107
	s_nop 1
	v_permlane16_swap_b32_e32 v108, v110
	v_permlane16_swap_b32_e32 v109, v111
	global_store_dwordx4 v[224:225], v[108:111], off offset:3584
	s_cbranch_scc0 .Lproj_nr_3
	v_pk_mul_f32 v[232:233], v[98:99], v[168:169]
	v_pk_mul_f32 v[234:235], v[96:97], v[166:167]
	v_pk_mul_f32 v[236:237], v[102:103], v[168:169]
	v_pk_mul_f32 v[238:239], v[100:101], v[166:167]
	v_pk_fma_f32 v[102:103], v[102:103], v[172:173], v[232:233] neg_lo:[0,0,1] neg_hi:[0,0,1]
	v_pk_fma_f32 v[100:101], v[100:101], v[170:171], v[234:235] neg_lo:[0,0,1] neg_hi:[0,0,1]
	v_pk_fma_f32 v[98:99], v[98:99], v[172:173], v[236:237]
	v_pk_fma_f32 v[96:97], v[96:97], v[170:171], v[238:239]
.Lproj_nr_3:
	v_cvt_pk_bf16_f32 v100, v100, v101
	v_cvt_pk_bf16_f32 v101, v102, v103
	v_cvt_pk_bf16_f32 v102, v96, v97
	v_cvt_pk_bf16_f32 v103, v98, v99
	s_nop 1
	v_permlane16_swap_b32_e32 v100, v102
	v_permlane16_swap_b32_e32 v101, v103
	global_store_dwordx4 v[224:225], v[100:103], off offset:3840
	s_cbranch_vccz .Lproj_nr_4
	v_pk_mul_f32 v[232:233], v[90:91], v[176:177]
	v_pk_mul_f32 v[234:235], v[88:89], v[174:175]
	v_pk_mul_f32 v[236:237], v[94:95], v[176:177]
	v_pk_mul_f32 v[238:239], v[92:93], v[174:175]
	v_pk_fma_f32 v[94:95], v[94:95], v[180:181], v[232:233] neg_lo:[0,0,1] neg_hi:[0,0,1]
	v_pk_fma_f32 v[92:93], v[92:93], v[178:179], v[234:235] neg_lo:[0,0,1] neg_hi:[0,0,1]
	v_pk_fma_f32 v[90:91], v[90:91], v[180:181], v[236:237]
	v_pk_fma_f32 v[88:89], v[88:89], v[178:179], v[238:239]
.Lproj_nr_4:
	v_cvt_pk_bf16_f32 v92, v92, v93
	v_cvt_pk_bf16_f32 v93, v94, v95
	v_cvt_pk_bf16_f32 v94, v88, v89
	v_cvt_pk_bf16_f32 v95, v90, v91
	s_nop 1
	v_permlane16_swap_b32_e32 v92, v94
	v_permlane16_swap_b32_e32 v93, v95
	global_store_dwordx4 v[226:227], v[92:95], off
	s_cbranch_scc0 .Lproj_nr_5
	v_pk_mul_f32 v[232:233], v[82:83], v[176:177]
	v_pk_mul_f32 v[234:235], v[80:81], v[174:175]
	v_pk_mul_f32 v[236:237], v[86:87], v[176:177]
	v_pk_mul_f32 v[238:239], v[84:85], v[174:175]
	v_pk_fma_f32 v[86:87], v[86:87], v[180:181], v[232:233] neg_lo:[0,0,1] neg_hi:[0,0,1]
	v_pk_fma_f32 v[84:85], v[84:85], v[178:179], v[234:235] neg_lo:[0,0,1] neg_hi:[0,0,1]
	v_pk_fma_f32 v[82:83], v[82:83], v[180:181], v[236:237]
	v_pk_fma_f32 v[80:81], v[80:81], v[178:179], v[238:239]
.Lproj_nr_5:
	v_cvt_pk_bf16_f32 v84, v84, v85
	v_cvt_pk_bf16_f32 v85, v86, v87
	v_cvt_pk_bf16_f32 v86, v80, v81
	v_cvt_pk_bf16_f32 v87, v82, v83
	s_nop 1
	v_permlane16_swap_b32_e32 v84, v86
	v_permlane16_swap_b32_e32 v85, v87
	global_store_dwordx4 v[226:227], v[84:87], off offset:256
	s_cbranch_vccz .Lproj_nr_6
	v_pk_mul_f32 v[232:233], v[74:75], v[184:185]
	v_pk_mul_f32 v[234:235], v[72:73], v[182:183]
	v_pk_mul_f32 v[236:237], v[78:79], v[184:185]
	v_pk_mul_f32 v[238:239], v[76:77], v[182:183]
	v_pk_fma_f32 v[78:79], v[78:79], v[188:189], v[232:233] neg_lo:[0,0,1] neg_hi:[0,0,1]
	v_pk_fma_f32 v[76:77], v[76:77], v[186:187], v[234:235] neg_lo:[0,0,1] neg_hi:[0,0,1]
	v_pk_fma_f32 v[74:75], v[74:75], v[188:189], v[236:237]
	v_pk_fma_f32 v[72:73], v[72:73], v[186:187], v[238:239]
; __device__ __forceinline__ unsigned pk2(float lo, float hi) { unsigned r; asm("v_cvt_pk_bf16_f32 %0, %1, %2" : "=v"(r) : "v"(lo), "v"(hi)); return r; }
;     __device__ __forceinline__ void operator()(const f32x4 (&acc)[2][2][4][2], const Unit& u, int wr, int wc, int fr, int fq) const {
;     ...
;                 for (int bj = 0; bj < 2; ++bj) {
;                     const int col = u.pn * 256 + bj * 128 + wc * 32 + 4 * fq;
;                     f32x4 v0 = acc[ai][bj][m][0], v1 = acc[ai][bj][m][1];
;                     const bool rope = latent && (u.pn == 4 || u.pn == 5 || (u.pn == 6 && bj == 0));
;                     if (rope) {
;                         const f32x4 cs = *(const f32x4*)(cosT + pos * 16 + 4 * fq), sn = *(const f32x4*)(sinT + pos * 16 + 4 * fq);
;                         const f32x4 n0 = v0 * cs - v1 * sn, n1 = v1 * cs + v0 * sn; v0 = n0; v1 = n1;
;                     }
;                     bf16_t* p = O + (size_t)row * DIN + col;
;                     u32x2 w0, w1; w0.x = pk2(v0[0], v0[1]); w0.y = pk2(v0[2], v0[3]); w1.x = pk2(v1[0], v1[1]); w1.y = pk2(v1[2], v1[3]);
;                     *(u32x2*)p = w0; *(u32x2*)(p + 16) = w1;
.Lproj_nr_6:
	v_cvt_pk_bf16_f32 v76, v76, v77
	v_cvt_pk_bf16_f32 v77, v78, v79
	v_cvt_pk_bf16_f32 v78, v72, v73
	v_cvt_pk_bf16_f32 v79, v74, v75
	s_nop 1
	v_permlane16_swap_b32_e32 v76, v78
	v_permlane16_swap_b32_e32 v77, v79
	global_store_dwordx4 v[226:227], v[76:79], off offset:3584
	s_cbranch_scc0 .Lproj_nr_7
	v_pk_mul_f32 v[232:233], v[66:67], v[184:185]
	v_pk_mul_f32 v[234:235], v[64:65], v[182:183]
	v_pk_mul_f32 v[236:237], v[70:71], v[184:185]
	v_pk_mul_f32 v[238:239], v[68:69], v[182:183]
	v_pk_fma_f32 v[70:71], v[70:71], v[188:189], v[232:233] neg_lo:[0,0,1] neg_hi:[0,0,1]
	v_pk_fma_f32 v[68:69], v[68:69], v[186:187], v[234:235] neg_lo:[0,0,1] neg_hi:[0,0,1]
	v_pk_fma_f32 v[66:67], v[66:67], v[188:189], v[236:237]
	v_pk_fma_f32 v[64:65], v[64:65], v[186:187], v[238:239]
.Lproj_nr_7:
	v_cvt_pk_bf16_f32 v68, v68, v69
	v_cvt_pk_bf16_f32 v69, v70, v71
	v_cvt_pk_bf16_f32 v70, v64, v65
	v_cvt_pk_bf16_f32 v71, v66, v67
	s_nop 1
	v_permlane16_swap_b32_e32 v68, v70
	v_permlane16_swap_b32_e32 v69, v71
	global_store_dwordx4 v[226:227], v[68:71], off offset:3840
	s_cbranch_vccz .Lproj_nr_8
	v_pk_mul_f32 v[232:233], v[58:59], v[192:193]
	v_pk_mul_f32 v[234:235], v[56:57], v[190:191]
	v_pk_mul_f32 v[236:237], v[62:63], v[192:193]
	v_pk_mul_f32 v[238:239], v[60:61], v[190:191]
	v_pk_fma_f32 v[62:63], v[62:63], v[196:197], v[232:233] neg_lo:[0,0,1] neg_hi:[0,0,1]
	v_pk_fma_f32 v[60:61], v[60:61], v[194:195], v[234:235] neg_lo:[0,0,1] neg_hi:[0,0,1]
	v_pk_fma_f32 v[58:59], v[58:59], v[196:197], v[236:237]
	v_pk_fma_f32 v[56:57], v[56:57], v[194:195], v[238:239]
.Lproj_nr_8:
	v_cvt_pk_bf16_f32 v60, v60, v61
	v_cvt_pk_bf16_f32 v61, v62, v63
	v_cvt_pk_bf16_f32 v62, v56, v57
	v_cvt_pk_bf16_f32 v63, v58, v59
	s_nop 1
	v_permlane16_swap_b32_e32 v60, v62
	v_permlane16_swap_b32_e32 v61, v63
	global_store_dwordx4 v[228:229], v[60:63], off
	s_cbranch_scc0 .Lproj_nr_9
	v_pk_mul_f32 v[232:233], v[50:51], v[192:193]
	v_pk_mul_f32 v[234:235], v[48:49], v[190:191]
	v_pk_mul_f32 v[236:237], v[54:55], v[192:193]
	v_pk_mul_f32 v[238:239], v[52:53], v[190:191]
	v_pk_fma_f32 v[54:55], v[54:55], v[196:197], v[232:233] neg_lo:[0,0,1] neg_hi:[0,0,1]
	v_pk_fma_f32 v[52:53], v[52:53], v[194:195], v[234:235] neg_lo:[0,0,1] neg_hi:[0,0,1]
	v_pk_fma_f32 v[50:51], v[50:51], v[196:197], v[236:237]
	v_pk_fma_f32 v[48:49], v[48:49], v[194:195], v[238:239]
.Lproj_nr_9:
	v_cvt_pk_bf16_f32 v52, v52, v53
	v_cvt_pk_bf16_f32 v53, v54, v55
	v_cvt_pk_bf16_f32 v54, v48, v49
	v_cvt_pk_bf16_f32 v55, v50, v51
	s_nop 1
	v_permlane16_swap_b32_e32 v52, v54
	v_permlane16_swap_b32_e32 v53, v55
	global_store_dwordx4 v[228:229], v[52:55], off offset:256
	s_cbranch_vccz .Lproj_nr_10
	v_pk_mul_f32 v[232:233], v[42:43], v[200:201]
	v_pk_mul_f32 v[234:235], v[40:41], v[198:199]
	v_pk_mul_f32 v[236:237], v[46:47], v[200:201]
	v_pk_mul_f32 v[238:239], v[44:45], v[198:199]
	v_pk_fma_f32 v[46:47], v[46:47], v[204:205], v[232:233] neg_lo:[0,0,1] neg_hi:[0,0,1]
	v_pk_fma_f32 v[44:45], v[44:45], v[202:203], v[234:235] neg_lo:[0,0,1] neg_hi:[0,0,1]
	v_pk_fma_f32 v[42:43], v[42:43], v[204:205], v[236:237]
	v_pk_fma_f32 v[40:41], v[40:41], v[202:203], v[238:239]
.Lproj_nr_10:
	v_cvt_pk_bf16_f32 v44, v44, v45
	v_cvt_pk_bf16_f32 v45, v46, v47
	v_cvt_pk_bf16_f32 v46, v40, v41
	v_cvt_pk_bf16_f32 v47, v42, v43
	s_nop 1
	v_permlane16_swap_b32_e32 v44, v46
	v_permlane16_swap_b32_e32 v45, v47
	global_store_dwordx4 v[228:229], v[44:47], off offset:3584
	s_cbranch_scc0 .Lproj_nr_11
	v_pk_mul_f32 v[232:233], v[34:35], v[200:201]
	v_pk_mul_f32 v[234:235], v[32:33], v[198:199]
	v_pk_mul_f32 v[236:237], v[38:39], v[200:201]
	v_pk_mul_f32 v[238:239], v[36:37], v[198:199]
	v_pk_fma_f32 v[38:39], v[38:39], v[204:205], v[232:233] neg_lo:[0,0,1] neg_hi:[0,0,1]
	v_pk_fma_f32 v[36:37], v[36:37], v[202:203], v[234:235] neg_lo:[0,0,1] neg_hi:[0,0,1]
	v_pk_fma_f32 v[34:35], v[34:35], v[204:205], v[236:237]
	v_pk_fma_f32 v[32:33], v[32:33], v[202:203], v[238:239]
; __device__ __forceinline__ unsigned pk2(float lo, float hi) { unsigned r; asm("v_cvt_pk_bf16_f32 %0, %1, %2" : "=v"(r) : "v"(lo), "v"(hi)); return r; }
;     __device__ __forceinline__ void operator()(const f32x4 (&acc)[2][2][4][2], const Unit& u, int wr, int wc, int fr, int fq) const {
;     ...
;                 for (int bj = 0; bj < 2; ++bj) {
;                     const int col = u.pn * 256 + bj * 128 + wc * 32 + 4 * fq;
;                     f32x4 v0 = acc[ai][bj][m][0], v1 = acc[ai][bj][m][1];
;                     const bool rope = latent && (u.pn == 4 || u.pn == 5 || (u.pn == 6 && bj == 0));
;                     if (rope) {
;                         const f32x4 cs = *(const f32x4*)(cosT + pos * 16 + 4 * fq), sn = *(const f32x4*)(sinT + pos * 16 + 4 * fq);
;                         const f32x4 n0 = v0 * cs - v1 * sn, n1 = v1 * cs + v0 * sn; v0 = n0; v1 = n1;
;                     }
;                     bf16_t* p = O + (size_t)row * DIN + col;
;                     u32x2 w0, w1; w0.x = pk2(v0[0], v0[1]); w0.y = pk2(v0[2], v0[3]); w1.x = pk2(v1[0], v1[1]); w1.y = pk2(v1[2], v1[3]);
;                     *(u32x2*)p = w0; *(u32x2*)(p + 16) = w1;
.Lproj_nr_11:
	v_cvt_pk_bf16_f32 v36, v36, v37
	v_cvt_pk_bf16_f32 v37, v38, v39
	v_cvt_pk_bf16_f32 v38, v32, v33
	v_cvt_pk_bf16_f32 v39, v34, v35
	s_nop 1
	v_permlane16_swap_b32_e32 v36, v38
	v_permlane16_swap_b32_e32 v37, v39
	global_store_dwordx4 v[228:229], v[36:39], off offset:3840
	s_cbranch_vccz .Lproj_nr_12
	v_pk_mul_f32 v[232:233], v[26:27], v[208:209]
	v_pk_mul_f32 v[234:235], v[24:25], v[206:207]
	v_pk_mul_f32 v[236:237], v[30:31], v[208:209]
	v_pk_mul_f32 v[238:239], v[28:29], v[206:207]
	v_pk_fma_f32 v[30:31], v[30:31], v[212:213], v[232:233] neg_lo:[0,0,1] neg_hi:[0,0,1]
	v_pk_fma_f32 v[28:29], v[28:29], v[210:211], v[234:235] neg_lo:[0,0,1] neg_hi:[0,0,1]
	v_pk_fma_f32 v[26:27], v[26:27], v[212:213], v[236:237]
	v_pk_fma_f32 v[24:25], v[24:25], v[210:211], v[238:239]
.Lproj_nr_12:
	v_cvt_pk_bf16_f32 v28, v28, v29
	v_cvt_pk_bf16_f32 v29, v30, v31
	v_cvt_pk_bf16_f32 v30, v24, v25
	v_cvt_pk_bf16_f32 v31, v26, v27
	s_nop 1
	v_permlane16_swap_b32_e32 v28, v30
	v_permlane16_swap_b32_e32 v29, v31
	global_store_dwordx4 v[230:231], v[28:31], off
	s_cbranch_scc0 .Lproj_nr_13
	v_pk_mul_f32 v[232:233], v[18:19], v[208:209]
	v_pk_mul_f32 v[234:235], v[16:17], v[206:207]
	v_pk_mul_f32 v[236:237], v[22:23], v[208:209]
	v_pk_mul_f32 v[238:239], v[20:21], v[206:207]
	v_pk_fma_f32 v[22:23], v[22:23], v[212:213], v[232:233] neg_lo:[0,0,1] neg_hi:[0,0,1]
	v_pk_fma_f32 v[20:21], v[20:21], v[210:211], v[234:235] neg_lo:[0,0,1] neg_hi:[0,0,1]
	v_pk_fma_f32 v[18:19], v[18:19], v[212:213], v[236:237]
	v_pk_fma_f32 v[16:17], v[16:17], v[210:211], v[238:239]
.Lproj_nr_13:
	v_cvt_pk_bf16_f32 v20, v20, v21
	v_cvt_pk_bf16_f32 v21, v22, v23
	v_cvt_pk_bf16_f32 v22, v16, v17
	v_cvt_pk_bf16_f32 v23, v18, v19
	s_nop 1
	v_permlane16_swap_b32_e32 v20, v22
	v_permlane16_swap_b32_e32 v21, v23
	global_store_dwordx4 v[230:231], v[20:23], off offset:256
	s_cbranch_vccz .Lproj_nr_14
	v_pk_mul_f32 v[232:233], v[10:11], v[216:217]
	v_pk_mul_f32 v[234:235], v[8:9], v[214:215]
	v_pk_mul_f32 v[236:237], v[14:15], v[216:217]
	v_pk_mul_f32 v[238:239], v[12:13], v[214:215]
	v_pk_fma_f32 v[14:15], v[14:15], v[220:221], v[232:233] neg_lo:[0,0,1] neg_hi:[0,0,1]
	v_pk_fma_f32 v[12:13], v[12:13], v[218:219], v[234:235] neg_lo:[0,0,1] neg_hi:[0,0,1]
	v_pk_fma_f32 v[10:11], v[10:11], v[220:221], v[236:237]
	v_pk_fma_f32 v[8:9], v[8:9], v[218:219], v[238:239]
.Lproj_nr_14:
	v_cvt_pk_bf16_f32 v12, v12, v13
	v_cvt_pk_bf16_f32 v13, v14, v15
	v_cvt_pk_bf16_f32 v14, v8, v9
	v_cvt_pk_bf16_f32 v15, v10, v11
	s_nop 1
	v_permlane16_swap_b32_e32 v12, v14
	v_permlane16_swap_b32_e32 v13, v15
	global_store_dwordx4 v[230:231], v[12:15], off offset:3584
	s_cbranch_scc0 .Lproj_nr_15
	v_pk_mul_f32 v[232:233], v[2:3], v[216:217]
	v_pk_mul_f32 v[234:235], v[0:1], v[214:215]
	v_pk_mul_f32 v[236:237], v[6:7], v[216:217]
	v_pk_mul_f32 v[238:239], v[4:5], v[214:215]
	v_pk_fma_f32 v[6:7], v[6:7], v[220:221], v[232:233] neg_lo:[0,0,1] neg_hi:[0,0,1]
	v_pk_fma_f32 v[4:5], v[4:5], v[218:219], v[234:235] neg_lo:[0,0,1] neg_hi:[0,0,1]
	v_pk_fma_f32 v[2:3], v[2:3], v[220:221], v[236:237]
	v_pk_fma_f32 v[0:1], v[0:1], v[218:219], v[238:239]
.Lproj_nr_15:
	v_cvt_pk_bf16_f32 v4, v4, v5
	v_cvt_pk_bf16_f32 v5, v6, v7
	v_cvt_pk_bf16_f32 v6, v0, v1
	v_cvt_pk_bf16_f32 v7, v2, v3
	s_nop 1
	v_permlane16_swap_b32_e32 v4, v6
	v_permlane16_swap_b32_e32 v5, v7
	global_store_dwordx4 v[230:231], v[4:7], off offset:3840
	s_branch .LBB0_207
